# in-GEMM B operand (WL_IN) also pair-interleaved: wconv_in stores and B-tile DMA addresses changed so every DMA instruction reads full 128B lines
# speedup vs baseline: 1.1064x; 1.0133x over previous
; DI int otid() { int t = threadIdx.x; asm volatile("" : "+v"(t)); return t; }
;   DI bf16* WL() const { return (bf16*)(p.ws + WS_WL); }
;   DI bf16* K() const { return (bf16*)(p.ws + WS_K); }
; DI void wconv_t(const float* W, int K, int N, int Npad, bf16* Wt) {
;   const size_t gt = (size_t)blockIdx.x * NT + otid(), gs = (size_t)gridDim.x * NT;
;   const int kc = K >> 3;
;   for (size_t i = gt; i < (size_t)Npad * kc; i += gs) {
;     const int n = (int)(i % Npad), k0 = (int)(i / Npad) * 8;
;     uint4 u = make_uint4(0, 0, 0, 0);
;     if (n < N) {
;       const float* w = W + (size_t)k0 * N + n;
;       u.x = pk2(w[0], w[(size_t)N]); u.y = pk2(w[(size_t)2 * N], w[(size_t)3 * N]);
;       u.z = pk2(w[(size_t)4 * N], w[(size_t)5 * N]); u.w = pk2(w[(size_t)6 * N], w[(size_t)7 * N]);
;     }
;     *(uint4*)(Wt + (size_t)n * K + k0) = u;
;   }
; DI void phase_wconv_in(const Ctx& c, int l) {
;   const Params& p = c.p; const int li = l >> 1;
;   if ((l & 1) == 0) wconv_t(p.even_w_in + (size_t)li * D * E_EVEN, D, E_EVEN, 2560, c.WL() + WL_IN / 2);
;   else wconv_t(p.odd_w_in + (size_t)li * D * E_ODD, D, E_ODD, 2560, c.WL() + WL_IN / 2);
.LBB0_70:
	s_or_b64 exec, exec, s[6:7]
	v_readlane_b32 s6, v252, 37
	v_readlane_b32 s7, v252, 38
	v_and_b32_e32 v20, 1, v8
	v_and_b32_e32 v8, -2, v8
	v_lshlrev_b64 v[10:11], 11, v[8:9]
	v_lshl_add_u64 v[10:11], s[52:53], 0, v[10:11]
	v_lshl_add_u64 v[6:7], v[6:7], 0, s[6:7]
	v_lshlrev_b32_e32 v8, 1, v1
	v_and_b32_e32 v21, 0xffffffc0, v8
	v_add_u32_e32 v8, v8, v21
	v_lshl_or_b32 v8, v20, 6, v8
	v_cmp_lt_u64_e32 vcc, s[4:5], v[6:7]
	v_lshl_add_u64 v[10:11], v[10:11], 0, v[8:9]
	s_or_b64 s[2:3], vcc, s[2:3]
	global_store_dwordx4 v[10:11], v[2:5], off
	s_andn2_b64 exec, exec, s[2:3]
	s_cbranch_execz .LBB0_73

; DI int otid() { int t = threadIdx.x; asm volatile("" : "+v"(t)); return t; }
;   DI bf16* K() const { return (bf16*)(p.ws + WS_K); }
; template <class AP, class BP, class Epi>
; DI void mfma_gemm_big_tile(const AP& aptr, const BP& bptr, int m0, int n0, int K, const Epi& epi, bf16* lds) {
;   const int tid = otid(), lane = tid & 63, wave = __builtin_amdgcn_readfirstlane(tid >> 6);
;   const int wm = (wave >> 1) * 128, wn = (wave & 1) * 64;
;   const int l16 = lane & 15, lq = lane >> 4;
;   const int lrow = tid >> 2, lcol = ((tid & 3) ^ ((-(tid >> 4)) & 3)) * 8;
;   const bf16* ap[4]; const bf16* bp[2];
; #pragma unroll
;   for (int i = 0; i < 4; ++i) ap[i] = aptr(m0 + lrow + 64 * i) + lcol;
; #pragma unroll
;   for (int i = 0; i < 2; ++i) bp[i] = bptr(n0 + lrow + 64 * i) + lcol;
;   f32x4 acc[8][4];
; #pragma unroll
;   for (int i = 0; i < 8; ++i)
; #pragma unroll
;     for (int j = 0; j < 4; ++j) acc[i][j] = f32x4{0.f, 0.f, 0.f, 0.f};
;   const int nk = K >> 5;
;     ...
;   BG_ISSUE(0, 0);
;   BG_ISSUE(1, 1);
.LBB0_248:
	s_mul_i32 s0, s8, s2
	s_add_i32 s0, s9, s0
	s_mul_hi_i32 s1, s0, 0x66666667
	s_lshr_b32 s4, s1, 31
	s_ashr_i32 s1, s1, 3
	v_mov_b32_e32 v26, v172
	s_add_i32 s1, s1, s4
	s_lshl_b32 s10, s1, 8
	v_lshrrev_b32_e32 v142, 4, v26
	s_mul_i32 s1, s1, 20
	v_sub_u32_e32 v27, 0, v142
	s_sub_i32 s0, s0, s1
	v_ashrrev_i32_e32 v18, 2, v26
	v_xor_b32_e32 v0, v26, v27
	s_lshl_b32 s11, s0, 7
	v_readfirstlane_b32 s0, v26
	v_add_u32_e32 v2, s10, v18
	v_lshlrev_b32_e32 v0, 4, v0
	s_and_b32 s12, s0, 64
	v_and_b32_e32 v0, 48, v0
	v_ashrrev_i32_e32 v3, 31, v2
	v_add_u32_e32 v10, 64, v2
	s_and_b32 s17, s0, 0xffffff80
	s_lshl_b32 s0, s0, 4
	v_lshl_add_u64 v[4:5], s[60:61], 0, v[0:1]
	v_bfe_u32 v30, v26, 2, 1
	v_mul_i32_i24_e32 v30, 0xfffff840, v30
	v_ashrrev_i32_e32 v31, 31, v30
	v_lshl_add_u64 v[4:5], v[4:5], 0, v[30:31]
	v_lshlrev_b64 v[6:7], 11, v[2:3]
	v_ashrrev_i32_e32 v11, 31, v10
	v_add_u32_e32 v14, 0x80, v2
	s_and_b32 s18, s0, 0xfffffc00
	v_lshl_add_u64 v[8:9], v[4:5], 0, v[6:7]
	v_lshlrev_b64 v[10:11], 11, v[10:11]
	v_ashrrev_i32_e32 v15, 31, v14
	v_add_u32_e32 v2, 0xc0, v2
	v_add_u32_e32 v18, s11, v18
	s_mov_b32 m0, s18
	v_lshl_add_u64 v[12:13], v[4:5], 0, v[10:11]
	v_lshlrev_b64 v[14:15], 11, v[14:15]
	v_ashrrev_i32_e32 v3, 31, v2
	v_ashrrev_i32_e32 v19, 31, v18
	global_load_lds_dwordx4 v[8:9], off
	s_add_i32 m0, s18, 0x1000
	v_lshl_add_u64 v[16:17], v[4:5], 0, v[14:15]
	v_lshlrev_b64 v[2:3], 11, v[2:3]
	v_lshlrev_b64 v[22:23], 11, v[18:19]
	v_add_u32_e32 v18, 64, v18
	global_load_lds_dwordx4 v[12:13], off
	s_add_i32 m0, s18, 0x2000
	v_lshl_add_u64 v[4:5], v[4:5], 0, v[2:3]
	v_lshl_add_u64 v[20:21], s[52:53], 0, v[0:1]
	v_lshl_add_u64 v[20:21], v[20:21], 0, v[30:31]
	v_ashrrev_i32_e32 v19, 31, v18
	global_load_lds_dwordx4 v[16:17], off
	s_add_i32 m0, s18, 0x3000
	v_lshl_add_u64 v[24:25], v[20:21], 0, v[22:23]
	v_lshlrev_b64 v[18:19], 11, v[18:19]
	global_load_lds_dwordx4 v[4:5], off
	s_add_i32 m0, s18, 0x4000
	v_lshl_add_u64 v[20:21], v[20:21], 0, v[18:19]
	global_load_lds_dwordx4 v[24:25], off
	s_add_i32 m0, s18, 0x5000
	v_lshl_add_u64 v[8:9], v[8:9], 0, 64
	v_lshl_add_u64 v[8:9], v[8:9], 0, 64
	global_load_lds_dwordx4 v[20:21], off
	s_add_i32 m0, s18, 0x6000
	v_lshl_add_u64 v[4:5], v[4:5], 0, 64
	v_lshl_add_u64 v[4:5], v[4:5], 0, 64
	global_load_lds_dwordx4 v[8:9], off
	v_lshl_add_u64 v[8:9], v[12:13], 0, 64
	v_lshl_add_u64 v[8:9], v[8:9], 0, 64
	s_add_i32 m0, s18, 0x7000
	v_and_b32_e32 v0, 15, v26
	global_load_lds_dwordx4 v[8:9], off
	v_lshl_add_u64 v[8:9], v[16:17], 0, 64
	v_lshl_add_u64 v[8:9], v[8:9], 0, 64
	s_add_i32 m0, s18, 0x8000
	v_readlane_b32 s0, v253, 53
	global_load_lds_dwordx4 v[8:9], off
	s_add_i32 m0, s18, 0x9000
	v_readlane_b32 s1, v253, 54
	global_load_lds_dwordx4 v[4:5], off
	v_lshl_add_u64 v[4:5], v[24:25], 0, 64
	v_lshl_add_u64 v[4:5], v[4:5], 0, 64
	s_add_i32 m0, s18, 0xa000
	s_mov_b32 s13, 2
	global_load_lds_dwordx4 v[4:5], off
	v_lshl_add_u64 v[4:5], v[20:21], 0, 64
	v_lshl_add_u64 v[4:5], v[4:5], 0, 64
	s_add_i32 m0, s18, 0xb000
	s_mov_b32 s16, 0
	global_load_lds_dwordx4 v[4:5], off
	v_lshrrev_b32_e32 v5, 2, v26
	v_sub_u32_e32 v5, 0, v5
	v_xor_b32_e32 v5, v142, v5
	v_lshlrev_b32_e32 v5, 4, v5
	v_or_b32_e32 v4, s17, v0
	v_and_b32_e32 v5, 48, v5
	v_lshl_or_b32 v143, v4, 6, v5
	v_or_b32_e32 v4, s12, v0
	v_lshlrev_b32_e32 v4, 6, v4
	v_or3_b32 v144, v5, v4, s77
	v_bitop3_b32 v4, v26, 3, v27 bitop3:0x48
	v_lshlrev_b32_e32 v4, 4, v4
	v_or_b32_e32 v18, v18, v4
	v_or_b32_e32 v22, v22, v4
	v_lshl_add_u64 v[130:131], s[0:1], 0, v[18:19]
	v_lshl_add_u64 v[132:133], s[0:1], 0, v[22:23]
	v_readlane_b32 s0, v253, 55
	s_waitcnt vmcnt(6)
	s_barrier
;   DI bf16* K() const { return (bf16*)(p.ws + WS_K); }
; template <class AP, class BP, class Epi>
; DI void mfma_gemm_big_tile(const AP& aptr, const BP& bptr, int m0, int n0, int K, const Epi& epi, bf16* lds) {
;     ...
;   const bf16* ap[4]; const bf16* bp[2];
; #pragma unroll
;   for (int i = 0; i < 4; ++i) ap[i] = aptr(m0 + lrow + 64 * i) + lcol;
; #pragma unroll
;   for (int i = 0; i < 2; ++i) bp[i] = bptr(n0 + lrow + 64 * i) + lcol;
;   f32x4 acc[8][4];
; #pragma unroll
;   for (int i = 0; i < 8; ++i)
; #pragma unroll
;     for (int j = 0; j < 4; ++j) acc[i][j] = f32x4{0.f, 0.f, 0.f, 0.f};
;   const int nk = K >> 5;
	v_or_b32_e32 v2, v2, v4
	v_readlane_b32 s1, v253, 56
	v_or_b32_e32 v14, v14, v4
	v_or_b32_e32 v10, v10, v4
	v_lshl_add_u64 v[134:135], s[0:1], 0, v[2:3]
	v_or_b32_e32 v6, v6, v4
	v_mov_b32_e32 v2, 0
	v_lshl_add_u64 v[136:137], s[0:1], 0, v[14:15]
	v_lshl_add_u64 v[138:139], s[0:1], 0, v[10:11]
	v_lshl_add_u64 v[140:141], s[0:1], 0, v[6:7]
	v_lshl_add_u64 v[30:31], v[30:31], 0, 64
	v_lshl_add_u64 v[30:31], v[30:31], 0, 64
	v_lshl_add_u64 v[130:131], v[130:131], 0, v[30:31]
	v_lshl_add_u64 v[132:133], v[132:133], 0, v[30:31]
	v_lshl_add_u64 v[134:135], v[134:135], 0, v[30:31]
	v_lshl_add_u64 v[136:137], v[136:137], 0, v[30:31]
	v_lshl_add_u64 v[138:139], v[138:139], 0, v[30:31]
	v_lshl_add_u64 v[140:141], v[140:141], 0, v[30:31]
	s_mov_b64 s[0:1], 0
	s_mov_b32 s19, 0
	v_mov_b32_e32 v3, v2
	v_mov_b32_e32 v4, v2
	v_mov_b32_e32 v5, v2
	v_mov_b32_e32 v6, v2
	v_mov_b32_e32 v7, v2
	v_mov_b32_e32 v8, v2
	v_mov_b32_e32 v9, v2
	v_mov_b32_e32 v10, v2
	v_mov_b32_e32 v11, v2
	v_mov_b32_e32 v12, v2
	v_mov_b32_e32 v13, v2
	v_mov_b32_e32 v14, v2
	v_mov_b32_e32 v15, v2
	v_mov_b32_e32 v16, v2
	v_mov_b32_e32 v17, v2
	v_mov_b32_e32 v18, v2
	v_mov_b32_e32 v19, v2
	v_mov_b32_e32 v20, v2
	v_mov_b32_e32 v21, v2
	v_mov_b32_e32 v22, v2
	v_mov_b32_e32 v23, v2
	v_mov_b32_e32 v24, v2
	v_mov_b32_e32 v25, v2
	v_mov_b32_e32 v26, v2
	v_mov_b32_e32 v27, v2
	v_mov_b32_e32 v28, v2
	v_mov_b32_e32 v29, v2
	v_mov_b32_e32 v30, v2
	v_mov_b32_e32 v31, v2
	v_mov_b32_e32 v32, v2
	v_mov_b32_e32 v33, v2
	v_mov_b32_e32 v34, v2
	v_mov_b32_e32 v35, v2
	v_mov_b32_e32 v36, v2
	v_mov_b32_e32 v37, v2
	v_mov_b32_e32 v38, v2
	v_mov_b32_e32 v39, v2
	v_mov_b32_e32 v40, v2
	v_mov_b32_e32 v41, v2
	v_mov_b32_e32 v42, v2
	v_mov_b32_e32 v43, v2
	v_mov_b32_e32 v44, v2
	v_mov_b32_e32 v45, v2
	v_mov_b32_e32 v46, v2
	v_mov_b32_e32 v47, v2
	v_mov_b32_e32 v48, v2
	v_mov_b32_e32 v49, v2
	v_mov_b32_e32 v50, v2
	v_mov_b32_e32 v51, v2
	v_mov_b32_e32 v52, v2
	v_mov_b32_e32 v53, v2
	v_mov_b32_e32 v54, v2
	v_mov_b32_e32 v55, v2
	v_mov_b32_e32 v56, v2
	v_mov_b32_e32 v57, v2
	v_mov_b32_e32 v58, v2
	v_mov_b32_e32 v59, v2
	v_mov_b32_e32 v60, v2
	v_mov_b32_e32 v61, v2
	v_mov_b32_e32 v62, v2
	v_mov_b32_e32 v63, v2
	v_mov_b32_e32 v64, v2
	v_mov_b32_e32 v65, v2
	v_mov_b32_e32 v66, v2
	v_mov_b32_e32 v67, v2
	v_mov_b32_e32 v68, v2
	v_mov_b32_e32 v69, v2
	v_mov_b32_e32 v70, v2
	v_mov_b32_e32 v71, v2
	v_mov_b32_e32 v72, v2
	v_mov_b32_e32 v73, v2
	v_mov_b32_e32 v74, v2
	v_mov_b32_e32 v75, v2
	v_mov_b32_e32 v76, v2
	v_mov_b32_e32 v77, v2
	v_mov_b32_e32 v78, v2
	v_mov_b32_e32 v79, v2
	v_mov_b32_e32 v80, v2
	v_mov_b32_e32 v81, v2
	v_mov_b32_e32 v82, v2
	v_mov_b32_e32 v83, v2
	v_mov_b32_e32 v84, v2
	v_mov_b32_e32 v85, v2
	v_mov_b32_e32 v86, v2
	v_mov_b32_e32 v87, v2
	v_mov_b32_e32 v88, v2
	v_mov_b32_e32 v89, v2
	v_mov_b32_e32 v90, v2
	v_mov_b32_e32 v91, v2
	v_mov_b32_e32 v92, v2
	v_mov_b32_e32 v93, v2
	v_mov_b32_e32 v94, v2
	v_mov_b32_e32 v95, v2
	v_mov_b32_e32 v96, v2
	v_mov_b32_e32 v97, v2
	v_mov_b32_e32 v98, v2
	v_mov_b32_e32 v99, v2
	v_mov_b32_e32 v100, v2
	v_mov_b32_e32 v101, v2
	v_mov_b32_e32 v102, v2
	v_mov_b32_e32 v103, v2
	v_mov_b32_e32 v104, v2
	v_mov_b32_e32 v105, v2
	v_mov_b32_e32 v106, v2
	v_mov_b32_e32 v107, v2
	v_mov_b32_e32 v108, v2
	v_mov_b32_e32 v109, v2
	v_mov_b32_e32 v110, v2
	v_mov_b32_e32 v111, v2
	v_mov_b32_e32 v112, v2
	v_mov_b32_e32 v113, v2
	v_mov_b32_e32 v114, v2
	v_mov_b32_e32 v115, v2
	v_mov_b32_e32 v116, v2
	v_mov_b32_e32 v117, v2
	v_mov_b32_e32 v118, v2
	v_mov_b32_e32 v119, v2
	v_mov_b32_e32 v120, v2
	v_mov_b32_e32 v121, v2
	v_mov_b32_e32 v122, v2
	v_mov_b32_e32 v123, v2
	v_mov_b32_e32 v124, v2
	v_mov_b32_e32 v125, v2
	v_mov_b32_e32 v126, v2
	v_mov_b32_e32 v127, v2
	v_mov_b32_e32 v128, v2
	v_mov_b32_e32 v129, v2
	s_branch .LBB0_250

; template <class AP, class BP, class Epi>
; DI void mfma_gemm_big_tile(const AP& aptr, const BP& bptr, int m0, int n0, int K, const Epi& epi, bf16* lds) {
;     ...
;   BG_ISSUE(0, 0);
;   BG_ISSUE(1, 1);
;   asm volatile("s_waitcnt vmcnt(6)\n\ts_barrier" ::: "memory");
;   const unsigned lbase = (unsigned)(size_t)lds;
;   const unsigned a_off = (unsigned)(((wm + l16) * 32 + (lq ^ ((-(l16 >> 2)) & 3)) * 8) * 2);
;   const unsigned b_off = (unsigned)((256 * 32 + (wn + l16) * 32 + (lq ^ ((-(l16 >> 2)) & 3)) * 8) * 2);
;     ...
;   int cur = 0, nxt = 2;
;   for (int ks = 0; ks < nk; ++ks) {
;     if (ks + 2 < nk) BG_ISSUE(nxt, ks + 2);
.LBB0_250:
	s_cmp_gt_u32 s16, 29
	s_cselect_b64 s[4:5], -1, 0
	s_and_b64 vcc, exec, s[4:5]
	s_cbranch_vccnz .LBB0_252
	s_mul_i32 s6, s13, 0x6000
	s_add_i32 s6, s18, s6
	v_lshl_add_u64 v[146:147], s[0:1], 1, v[140:141]
	s_mov_b32 m0, s6
	s_nop 0
	global_load_lds_dwordx4 v[146:147], off
	v_lshl_add_u64 v[146:147], s[0:1], 1, v[138:139]
	s_add_i32 m0, s6, 0x1000
	s_nop 0
	global_load_lds_dwordx4 v[146:147], off
	v_lshl_add_u64 v[146:147], s[0:1], 1, v[136:137]
	s_add_i32 m0, s6, 0x2000
	s_nop 0
	global_load_lds_dwordx4 v[146:147], off
	v_lshl_add_u64 v[146:147], s[0:1], 1, v[134:135]
	s_add_i32 m0, s6, 0x3000
	s_nop 0
	global_load_lds_dwordx4 v[146:147], off
	v_lshl_add_u64 v[146:147], s[0:1], 1, v[132:133]
	s_add_i32 m0, s6, 0x4000
	s_nop 0
	global_load_lds_dwordx4 v[146:147], off
	v_lshl_add_u64 v[146:147], s[0:1], 1, v[130:131]
	s_add_i32 m0, s6, 0x5000
	s_nop 0
	global_load_lds_dwordx4 v[146:147], off

; DI int otid() { int t = threadIdx.x; asm volatile("" : "+v"(t)); return t; }
;   DI bf16* K() const { return (bf16*)(p.ws + WS_K); }
; template <class AP, class BP, class Epi>
; DI void mfma_gemm_big_tile(const AP& aptr, const BP& bptr, int m0, int n0, int K, const Epi& epi, bf16* lds) {
;   const int tid = otid(), lane = tid & 63, wave = __builtin_amdgcn_readfirstlane(tid >> 6);
;   const int wm = (wave >> 1) * 128, wn = (wave & 1) * 64;
;   const int l16 = lane & 15, lq = lane >> 4;
;   const int lrow = tid >> 2, lcol = ((tid & 3) ^ ((-(tid >> 4)) & 3)) * 8;
;   const bf16* ap[4]; const bf16* bp[2];
; #pragma unroll
;   for (int i = 0; i < 4; ++i) ap[i] = aptr(m0 + lrow + 64 * i) + lcol;
; #pragma unroll
;   for (int i = 0; i < 2; ++i) bp[i] = bptr(n0 + lrow + 64 * i) + lcol;
;   f32x4 acc[8][4];
; #pragma unroll
;   for (int i = 0; i < 8; ++i)
; #pragma unroll
;     for (int j = 0; j < 4; ++j) acc[i][j] = f32x4{0.f, 0.f, 0.f, 0.f};
;   const int nk = K >> 5;
;     ...
;   BG_ISSUE(0, 0);
;   BG_ISSUE(1, 1);
.LBB0_508:
	s_mul_i32 s0, s8, s2
	s_add_i32 s0, s9, s0
	s_mul_hi_i32 s1, s0, 0x66666667
	s_lshr_b32 s4, s1, 31
	s_ashr_i32 s1, s1, 3
	v_mov_b32_e32 v26, v172
	s_add_i32 s1, s1, s4
	s_lshl_b32 s10, s1, 8
	v_lshrrev_b32_e32 v142, 4, v26
	s_mul_i32 s1, s1, 20
	v_sub_u32_e32 v27, 0, v142
	s_sub_i32 s0, s0, s1
	v_ashrrev_i32_e32 v18, 2, v26
	v_xor_b32_e32 v0, v26, v27
	s_lshl_b32 s11, s0, 7
	v_readfirstlane_b32 s0, v26
	v_add_u32_e32 v2, s10, v18
	v_lshlrev_b32_e32 v0, 4, v0
	s_and_b32 s12, s0, 64
	v_and_b32_e32 v0, 48, v0
	v_ashrrev_i32_e32 v3, 31, v2
	v_add_u32_e32 v10, 64, v2
	s_and_b32 s16, s0, 0xffffff80
	s_lshl_b32 s0, s0, 4
	v_lshl_add_u64 v[4:5], s[60:61], 0, v[0:1]
	v_bfe_u32 v30, v26, 2, 1
	v_mul_i32_i24_e32 v30, 0xfffff840, v30
	v_ashrrev_i32_e32 v31, 31, v30
	v_lshl_add_u64 v[4:5], v[4:5], 0, v[30:31]
	v_lshlrev_b64 v[6:7], 11, v[2:3]
	v_ashrrev_i32_e32 v11, 31, v10
	v_add_u32_e32 v14, 0x80, v2
	s_and_b32 s17, s0, 0xfffffc00
	v_lshl_add_u64 v[8:9], v[4:5], 0, v[6:7]
	v_lshlrev_b64 v[10:11], 11, v[10:11]
	v_ashrrev_i32_e32 v15, 31, v14
	v_add_u32_e32 v2, 0xc0, v2
	v_add_u32_e32 v18, s11, v18
	s_mov_b32 m0, s17
	v_lshl_add_u64 v[12:13], v[4:5], 0, v[10:11]
	v_lshlrev_b64 v[14:15], 11, v[14:15]
	v_ashrrev_i32_e32 v3, 31, v2
	v_ashrrev_i32_e32 v19, 31, v18
	global_load_lds_dwordx4 v[8:9], off
	s_add_i32 m0, s17, 0x1000
	v_lshl_add_u64 v[16:17], v[4:5], 0, v[14:15]
	v_lshlrev_b64 v[2:3], 11, v[2:3]
	v_lshlrev_b64 v[22:23], 11, v[18:19]
	v_add_u32_e32 v18, 64, v18
	global_load_lds_dwordx4 v[12:13], off
	s_add_i32 m0, s17, 0x2000
	v_lshl_add_u64 v[4:5], v[4:5], 0, v[2:3]
	v_lshl_add_u64 v[20:21], s[52:53], 0, v[0:1]
	v_lshl_add_u64 v[20:21], v[20:21], 0, v[30:31]
	v_ashrrev_i32_e32 v19, 31, v18
	global_load_lds_dwordx4 v[16:17], off
	s_add_i32 m0, s17, 0x3000
	v_lshl_add_u64 v[24:25], v[20:21], 0, v[22:23]
	v_lshlrev_b64 v[18:19], 11, v[18:19]
	global_load_lds_dwordx4 v[4:5], off
	s_add_i32 m0, s17, 0x4000
	v_lshl_add_u64 v[20:21], v[20:21], 0, v[18:19]
	global_load_lds_dwordx4 v[24:25], off
	s_add_i32 m0, s17, 0x5000
	v_lshl_add_u64 v[8:9], v[8:9], 0, 64
	v_lshl_add_u64 v[8:9], v[8:9], 0, 64
	global_load_lds_dwordx4 v[20:21], off
	s_add_i32 m0, s17, 0x6000
	v_lshl_add_u64 v[4:5], v[4:5], 0, 64
	v_lshl_add_u64 v[4:5], v[4:5], 0, 64
	global_load_lds_dwordx4 v[8:9], off
	v_lshl_add_u64 v[8:9], v[12:13], 0, 64
	v_lshl_add_u64 v[8:9], v[8:9], 0, 64
	s_add_i32 m0, s17, 0x7000
	v_and_b32_e32 v0, 15, v26
	global_load_lds_dwordx4 v[8:9], off
	v_lshl_add_u64 v[8:9], v[16:17], 0, 64
	v_lshl_add_u64 v[8:9], v[8:9], 0, 64
	s_add_i32 m0, s17, 0x8000
	v_readlane_b32 s0, v253, 53
	global_load_lds_dwordx4 v[8:9], off
	s_add_i32 m0, s17, 0x9000
	v_readlane_b32 s1, v253, 54
	global_load_lds_dwordx4 v[4:5], off
	v_lshl_add_u64 v[4:5], v[24:25], 0, 64
	v_lshl_add_u64 v[4:5], v[4:5], 0, 64
	s_add_i32 m0, s17, 0xa000
	s_mov_b32 s13, 2
	global_load_lds_dwordx4 v[4:5], off
	v_lshl_add_u64 v[4:5], v[20:21], 0, 64
	v_lshl_add_u64 v[4:5], v[4:5], 0, 64
	s_add_i32 m0, s17, 0xb000
	s_mov_b32 s15, 0
	global_load_lds_dwordx4 v[4:5], off
	v_lshrrev_b32_e32 v5, 2, v26
	v_sub_u32_e32 v5, 0, v5
	v_xor_b32_e32 v5, v142, v5
	v_lshlrev_b32_e32 v5, 4, v5
	v_or_b32_e32 v4, s16, v0
	v_and_b32_e32 v5, 48, v5
	v_lshl_or_b32 v143, v4, 6, v5
	v_or_b32_e32 v4, s12, v0
	v_lshlrev_b32_e32 v4, 6, v4
	v_or3_b32 v144, v5, v4, s77
	v_bitop3_b32 v4, v26, 3, v27 bitop3:0x48
	v_lshlrev_b32_e32 v4, 4, v4
	v_or_b32_e32 v18, v18, v4
	v_or_b32_e32 v22, v22, v4
	v_lshl_add_u64 v[130:131], s[0:1], 0, v[18:19]
	v_lshl_add_u64 v[132:133], s[0:1], 0, v[22:23]
	v_readlane_b32 s0, v253, 55
	s_waitcnt vmcnt(6)
	s_barrier
;   DI bf16* K() const { return (bf16*)(p.ws + WS_K); }
; template <class AP, class BP, class Epi>
; DI void mfma_gemm_big_tile(const AP& aptr, const BP& bptr, int m0, int n0, int K, const Epi& epi, bf16* lds) {
;     ...
;   const bf16* ap[4]; const bf16* bp[2];
; #pragma unroll
;   for (int i = 0; i < 4; ++i) ap[i] = aptr(m0 + lrow + 64 * i) + lcol;
; #pragma unroll
;   for (int i = 0; i < 2; ++i) bp[i] = bptr(n0 + lrow + 64 * i) + lcol;
;   f32x4 acc[8][4];
; #pragma unroll
;   for (int i = 0; i < 8; ++i)
; #pragma unroll
;     for (int j = 0; j < 4; ++j) acc[i][j] = f32x4{0.f, 0.f, 0.f, 0.f};
;   const int nk = K >> 5;
	v_or_b32_e32 v2, v2, v4
	v_readlane_b32 s1, v253, 56
	v_or_b32_e32 v14, v14, v4
	v_or_b32_e32 v10, v10, v4
	v_lshl_add_u64 v[134:135], s[0:1], 0, v[2:3]
	v_or_b32_e32 v6, v6, v4
	v_mov_b32_e32 v2, 0
	v_lshl_add_u64 v[136:137], s[0:1], 0, v[14:15]
	v_lshl_add_u64 v[138:139], s[0:1], 0, v[10:11]
	v_lshl_add_u64 v[140:141], s[0:1], 0, v[6:7]
	v_lshl_add_u64 v[30:31], v[30:31], 0, 64
	v_lshl_add_u64 v[30:31], v[30:31], 0, 64
	v_lshl_add_u64 v[130:131], v[130:131], 0, v[30:31]
	v_lshl_add_u64 v[132:133], v[132:133], 0, v[30:31]
	v_lshl_add_u64 v[134:135], v[134:135], 0, v[30:31]
	v_lshl_add_u64 v[136:137], v[136:137], 0, v[30:31]
	v_lshl_add_u64 v[138:139], v[138:139], 0, v[30:31]
	v_lshl_add_u64 v[140:141], v[140:141], 0, v[30:31]
	s_mov_b64 s[0:1], 0
	s_mov_b32 s18, 0
	v_mov_b32_e32 v3, v2
	v_mov_b32_e32 v4, v2
	v_mov_b32_e32 v5, v2
	v_mov_b32_e32 v6, v2
	v_mov_b32_e32 v7, v2
	v_mov_b32_e32 v8, v2
	v_mov_b32_e32 v9, v2
	v_mov_b32_e32 v10, v2
	v_mov_b32_e32 v11, v2
	v_mov_b32_e32 v12, v2
	v_mov_b32_e32 v13, v2
	v_mov_b32_e32 v14, v2
	v_mov_b32_e32 v15, v2
	v_mov_b32_e32 v16, v2
	v_mov_b32_e32 v17, v2
	v_mov_b32_e32 v18, v2
	v_mov_b32_e32 v19, v2
	v_mov_b32_e32 v20, v2
	v_mov_b32_e32 v21, v2
	v_mov_b32_e32 v22, v2
	v_mov_b32_e32 v23, v2
	v_mov_b32_e32 v24, v2
	v_mov_b32_e32 v25, v2
	v_mov_b32_e32 v26, v2
	v_mov_b32_e32 v27, v2
	v_mov_b32_e32 v28, v2
	v_mov_b32_e32 v29, v2
	v_mov_b32_e32 v30, v2
	v_mov_b32_e32 v31, v2
	v_mov_b32_e32 v32, v2
	v_mov_b32_e32 v33, v2
	v_mov_b32_e32 v34, v2
	v_mov_b32_e32 v35, v2
	v_mov_b32_e32 v36, v2
	v_mov_b32_e32 v37, v2
	v_mov_b32_e32 v38, v2
	v_mov_b32_e32 v39, v2
	v_mov_b32_e32 v40, v2
	v_mov_b32_e32 v41, v2
	v_mov_b32_e32 v42, v2
	v_mov_b32_e32 v43, v2
	v_mov_b32_e32 v44, v2
	v_mov_b32_e32 v45, v2
	v_mov_b32_e32 v46, v2
	v_mov_b32_e32 v47, v2
	v_mov_b32_e32 v48, v2
	v_mov_b32_e32 v49, v2
	v_mov_b32_e32 v50, v2
	v_mov_b32_e32 v51, v2
	v_mov_b32_e32 v52, v2
	v_mov_b32_e32 v53, v2
	v_mov_b32_e32 v54, v2
	v_mov_b32_e32 v55, v2
	v_mov_b32_e32 v56, v2
	v_mov_b32_e32 v57, v2
	v_mov_b32_e32 v58, v2
	v_mov_b32_e32 v59, v2
	v_mov_b32_e32 v60, v2
	v_mov_b32_e32 v61, v2
	v_mov_b32_e32 v62, v2
	v_mov_b32_e32 v63, v2
	v_mov_b32_e32 v64, v2
	v_mov_b32_e32 v65, v2
	v_mov_b32_e32 v66, v2
	v_mov_b32_e32 v67, v2
	v_mov_b32_e32 v68, v2
	v_mov_b32_e32 v69, v2
	v_mov_b32_e32 v70, v2
	v_mov_b32_e32 v71, v2
	v_mov_b32_e32 v72, v2
	v_mov_b32_e32 v73, v2
	v_mov_b32_e32 v74, v2
	v_mov_b32_e32 v75, v2
	v_mov_b32_e32 v76, v2
	v_mov_b32_e32 v77, v2
	v_mov_b32_e32 v78, v2
	v_mov_b32_e32 v79, v2
	v_mov_b32_e32 v80, v2
	v_mov_b32_e32 v81, v2
	v_mov_b32_e32 v82, v2
	v_mov_b32_e32 v83, v2
	v_mov_b32_e32 v84, v2
	v_mov_b32_e32 v85, v2
	v_mov_b32_e32 v86, v2
	v_mov_b32_e32 v87, v2
	v_mov_b32_e32 v88, v2
	v_mov_b32_e32 v89, v2
	v_mov_b32_e32 v90, v2
	v_mov_b32_e32 v91, v2
	v_mov_b32_e32 v92, v2
	v_mov_b32_e32 v93, v2
	v_mov_b32_e32 v94, v2
	v_mov_b32_e32 v95, v2
	v_mov_b32_e32 v96, v2
	v_mov_b32_e32 v97, v2
	v_mov_b32_e32 v98, v2
	v_mov_b32_e32 v99, v2
	v_mov_b32_e32 v100, v2
	v_mov_b32_e32 v101, v2
	v_mov_b32_e32 v102, v2
	v_mov_b32_e32 v103, v2
	v_mov_b32_e32 v104, v2
	v_mov_b32_e32 v105, v2
	v_mov_b32_e32 v106, v2
	v_mov_b32_e32 v107, v2
	v_mov_b32_e32 v108, v2
	v_mov_b32_e32 v109, v2
	v_mov_b32_e32 v110, v2
	v_mov_b32_e32 v111, v2
	v_mov_b32_e32 v112, v2
	v_mov_b32_e32 v113, v2
	v_mov_b32_e32 v114, v2
	v_mov_b32_e32 v115, v2
	v_mov_b32_e32 v116, v2
	v_mov_b32_e32 v117, v2
	v_mov_b32_e32 v118, v2
	v_mov_b32_e32 v119, v2
	v_mov_b32_e32 v120, v2
	v_mov_b32_e32 v121, v2
	v_mov_b32_e32 v122, v2
	v_mov_b32_e32 v123, v2
	v_mov_b32_e32 v124, v2
	v_mov_b32_e32 v125, v2
	v_mov_b32_e32 v126, v2
	v_mov_b32_e32 v127, v2
	v_mov_b32_e32 v128, v2
	v_mov_b32_e32 v129, v2
	s_branch .LBB0_510

; template <class AP, class BP, class Epi>
; DI void mfma_gemm_big_tile(const AP& aptr, const BP& bptr, int m0, int n0, int K, const Epi& epi, bf16* lds) {
;     ...
;   BG_ISSUE(0, 0);
;   BG_ISSUE(1, 1);
;   asm volatile("s_waitcnt vmcnt(6)\n\ts_barrier" ::: "memory");
;   const unsigned lbase = (unsigned)(size_t)lds;
;   const unsigned a_off = (unsigned)(((wm + l16) * 32 + (lq ^ ((-(l16 >> 2)) & 3)) * 8) * 2);
;   const unsigned b_off = (unsigned)((256 * 32 + (wn + l16) * 32 + (lq ^ ((-(l16 >> 2)) & 3)) * 8) * 2);
;     ...
;   int cur = 0, nxt = 2;
;   for (int ks = 0; ks < nk; ++ks) {
;     if (ks + 2 < nk) BG_ISSUE(nxt, ks + 2);
.LBB0_510:
	s_cmp_gt_u32 s15, 29
	s_cselect_b64 s[4:5], -1, 0
	s_and_b64 vcc, exec, s[4:5]
	s_cbranch_vccnz .LBB0_512
	s_mul_i32 s6, s13, 0x6000
	s_add_i32 s6, s17, s6
	v_lshl_add_u64 v[146:147], s[0:1], 1, v[140:141]
	s_mov_b32 m0, s6
	s_nop 0
	global_load_lds_dwordx4 v[146:147], off
	v_lshl_add_u64 v[146:147], s[0:1], 1, v[138:139]
	s_add_i32 m0, s6, 0x1000
	s_nop 0
	global_load_lds_dwordx4 v[146:147], off
	v_lshl_add_u64 v[146:147], s[0:1], 1, v[136:137]
	s_add_i32 m0, s6, 0x2000
	s_nop 0
	global_load_lds_dwordx4 v[146:147], off
	v_lshl_add_u64 v[146:147], s[0:1], 1, v[134:135]
	s_add_i32 m0, s6, 0x3000
	s_nop 0
	global_load_lds_dwordx4 v[146:147], off
	v_lshl_add_u64 v[146:147], s[0:1], 1, v[132:133]
	s_add_i32 m0, s6, 0x4000
	s_nop 0
	global_load_lds_dwordx4 v[146:147], off
	v_lshl_add_u64 v[146:147], s[0:1], 1, v[130:131]
	s_add_i32 m0, s6, 0x5000
	s_nop 0
	global_load_lds_dwordx4 v[146:147], off

; DI int otid() { int t = threadIdx.x; asm volatile("" : "+v"(t)); return t; }
;   DI bf16* K() const { return (bf16*)(p.ws + WS_K); }
; DI void wconv_t(const float* W, int K, int N, int Npad, bf16* Wt) {
;   const size_t gt = (size_t)blockIdx.x * NT + otid(), gs = (size_t)gridDim.x * NT;
;   const int kc = K >> 3;
;   for (size_t i = gt; i < (size_t)Npad * kc; i += gs) {
;     const int n = (int)(i % Npad), k0 = (int)(i / Npad) * 8;
;     uint4 u = make_uint4(0, 0, 0, 0);
;     if (n < N) {
;       const float* w = W + (size_t)k0 * N + n;
;       u.x = pk2(w[0], w[(size_t)N]); u.y = pk2(w[(size_t)2 * N], w[(size_t)3 * N]);
;       u.z = pk2(w[(size_t)4 * N], w[(size_t)5 * N]); u.w = pk2(w[(size_t)6 * N], w[(size_t)7 * N]);
;     }
;     *(uint4*)(Wt + (size_t)n * K + k0) = u;
;   }
.LBB0_1079:
	s_or_b64 exec, exec, s[12:13]
	v_and_b32_e32 v20, 1, v0
	v_and_b32_e32 v0, -2, v0
	v_lshlrev_b64 v[10:11], 11, v[0:1]
	v_lshl_add_u64 v[6:7], v[6:7], 0, s[8:9]
	v_lshl_add_u64 v[10:11], s[52:53], 0, v[10:11]
	v_lshlrev_b32_e32 v0, 1, v8
	v_and_b32_e32 v21, 0xffffffc0, v0
	v_add_u32_e32 v0, v0, v21
	v_lshl_or_b32 v0, v20, 6, v0
	v_cmp_lt_u64_e32 vcc, s[38:39], v[6:7]
	v_lshl_add_u64 v[8:9], v[10:11], 0, v[0:1]
	s_or_b64 s[10:11], vcc, s[10:11]
	global_store_dwordx4 v[8:9], v[2:5], off
	s_andn2_b64 exec, exec, s[10:11]
	s_cbranch_execz .LBB0_1082

; DI int otid() { int t = threadIdx.x; asm volatile("" : "+v"(t)); return t; }
;   DI bf16* WL() const { return (bf16*)(p.ws + WS_WL); }
;   DI bf16* K() const { return (bf16*)(p.ws + WS_K); }
; DI void wconv_t(const float* W, int K, int N, int Npad, bf16* Wt) {
;   const size_t gt = (size_t)blockIdx.x * NT + otid(), gs = (size_t)gridDim.x * NT;
;   const int kc = K >> 3;
;   for (size_t i = gt; i < (size_t)Npad * kc; i += gs) {
;     const int n = (int)(i % Npad), k0 = (int)(i / Npad) * 8;
;     uint4 u = make_uint4(0, 0, 0, 0);
;     if (n < N) {
;       const float* w = W + (size_t)k0 * N + n;
;       u.x = pk2(w[0], w[(size_t)N]); u.y = pk2(w[(size_t)2 * N], w[(size_t)3 * N]);
;       u.z = pk2(w[(size_t)4 * N], w[(size_t)5 * N]); u.w = pk2(w[(size_t)6 * N], w[(size_t)7 * N]);
;     }
;     *(uint4*)(Wt + (size_t)n * K + k0) = u;
;   }
; DI void phase_wconv_in(const Ctx& c, int l) {
;   const Params& p = c.p; const int li = l >> 1;
;   if ((l & 1) == 0) wconv_t(p.even_w_in + (size_t)li * D * E_EVEN, D, E_EVEN, 2560, c.WL() + WL_IN / 2);
;   else wconv_t(p.odd_w_in + (size_t)li * D * E_ODD, D, E_ODD, 2560, c.WL() + WL_IN / 2);
.LBB0_1086:
	v_mul_hi_u32 v0, v2, s2
	v_lshrrev_b32_e32 v8, 11, v0
	v_mul_u32_u24_e32 v0, 0xa00, v8
	v_lshlrev_b32_e32 v6, 3, v8
	v_mov_b64_e32 v[4:5], s[6:7]
	s_movk_i32 s12, 0x2800
	v_sub_u32_e32 v0, v2, v0
	v_mad_u64_u32 v[4:5], s[12:13], v6, s12, v[4:5]
	v_lshl_add_u64 v[4:5], v[0:1], 2, v[4:5]
	v_add_co_u32_e32 v6, vcc, 0x2000, v4
	global_load_dword v10, v[4:5], off
	s_nop 0
	v_addc_co_u32_e32 v7, vcc, 0, v5, vcc
	global_load_dword v11, v[6:7], off offset:2048
	v_add_co_u32_e32 v6, vcc, 0x5000, v4
	v_lshl_add_u64 v[2:3], v[2:3], 0, s[8:9]
	s_nop 0
	v_addc_co_u32_e32 v7, vcc, 0, v5, vcc
	global_load_dword v12, v[6:7], off
	v_add_co_u32_e32 v6, vcc, 0x7000, v4
	s_nop 1
	v_addc_co_u32_e32 v7, vcc, 0, v5, vcc
	global_load_dword v13, v[6:7], off offset:2048
	v_add_co_u32_e32 v6, vcc, 0xa000, v4
	s_nop 1
	v_addc_co_u32_e32 v7, vcc, 0, v5, vcc
	global_load_dword v14, v[6:7], off
	v_add_co_u32_e32 v6, vcc, 0xc000, v4
	s_nop 1
	v_addc_co_u32_e32 v7, vcc, 0, v5, vcc
	global_load_dword v15, v[6:7], off offset:2048
	v_add_co_u32_e32 v6, vcc, 0xf000, v4
	s_nop 1
	v_addc_co_u32_e32 v7, vcc, 0, v5, vcc
	v_add_co_u32_e32 v4, vcc, 0x11000, v4
	global_load_dword v6, v[6:7], off
	s_nop 0
	v_addc_co_u32_e32 v5, vcc, 0, v5, vcc
	global_load_dword v7, v[4:5], off offset:2048
	v_and_b32_e32 v20, 1, v0
	v_and_b32_e32 v0, -2, v0
	v_lshlrev_b64 v[4:5], 11, v[0:1]
	v_lshl_add_u64 v[4:5], s[52:53], 0, v[4:5]
	v_lshlrev_b32_e32 v0, 4, v8
	v_and_b32_e32 v21, 0xffffffc0, v0
	v_add_u32_e32 v0, v0, v21
	v_lshl_or_b32 v0, v20, 6, v0
	v_cmp_lt_u64_e32 vcc, s[38:39], v[2:3]
	v_lshl_add_u64 v[8:9], v[4:5], 0, v[0:1]
	s_or_b64 s[10:11], vcc, s[10:11]
	s_waitcnt vmcnt(6)
	v_cvt_pk_bf16_f32 v4, v10, v11
	s_waitcnt vmcnt(4)
	v_cvt_pk_bf16_f32 v5, v12, v13
	s_waitcnt vmcnt(0)
	v_cvt_pk_bf16_f32 v7, v6, v7
	v_cvt_pk_bf16_f32 v6, v14, v15
	global_store_dwordx4 v[8:9], v[4:7], off
	s_andn2_b64 exec, exec, s[10:11]
	s_cbranch_execnz .LBB0_1086
